# v12 + static s_setprio 1 for waves 0-3 during attention
# baseline (speedup 1.0000x reference)
; #define PHASE_IDS() int tid = wave * 64 + lane_id(); asm volatile("" : "+v"(tid)); const int lane = tid & 63, gt = vcu * 512 + tid; (void)lane; (void)gt
; template <int DQK, bool CAUSAL, bool ROPE> ...
;     ...
;     u32x4 sk[2], sk2 = {0u, 0u, 0u, 0u}, sv[2];
;     const unsigned bkA = (unsigned)((tid >> 4) * ldk1 + (tid & 15) * 8) * 2u, bkB = bkA + (unsigned)(32 * ldk1) * 2u;
;     const unsigned bk2 = (unsigned)((tid >> 3) * ldk2 + (tid & 7) * 8) * 2u;
;     const unsigned bvA = (unsigned)((tid >> 3) * ldvt + (tid & 7) * 8) * 2u, bvB = bvA + (unsigned)(64 * ldvt) * 2u;
;     ...
;     AT_LOAD(0); AT_STORE(0, 0);
;     __syncthreads();
;     const int pm_ = (c & 3) | ((c & 4) << 1) | ((c & 8) >> 1) | (c & 16);
;     const int koff = pm_ * KROW + hi * 16, voff = VBASE + c * VROW + hi * 16;
; __global__ void __launch_bounds__(512, 2) fwd_kernel(Args args) {
;     ...
;     if (IN(6)) {
;         PHASE_IDS();
;         const float C = 0.07216878364870322f * LOG2E;
;         for (int it = vcu; it < NB * NH * 16; it += G) {
.LBB0_878:
	v_writelane_b32 v255, s62, 10
	v_writelane_b32 v254, s72, 58
	s_add_u32 s0, s96, 0x3000000
	v_writelane_b32 v255, s63, 11
	v_writelane_b32 v255, s95, 12
	v_writelane_b32 v255, s94, 13
	v_writelane_b32 v254, s73, 59
	v_writelane_b32 v254, s74, 60
	v_writelane_b32 v255, s95, 14
	v_writelane_b32 v255, s92, 15
	v_writelane_b32 v254, s75, 61
	v_writelane_b32 v254, s76, 62
	v_writelane_b32 v255, s93, 16
	v_writelane_b32 v255, s78, 0
	v_writelane_b32 v255, s79, 1
	v_writelane_b32 v255, s80, 2
	v_writelane_b32 v255, s81, 3
	v_writelane_b32 v255, s82, 4
	v_writelane_b32 v255, s83, 5
	v_writelane_b32 v255, s84, 6
	v_writelane_b32 v255, s85, 7
	v_writelane_b32 v254, s77, 63
	v_writelane_b32 v255, s86, 8
	v_writelane_b32 v255, s87, 9
	v_writelane_b32 v254, s0, 20
	s_mov_b32 s0, s73
	s_addc_u32 s73, s97, 0
	s_add_u32 s1, s96, 0x15000000
	s_addc_u32 s74, s97, 0
	s_add_u32 s75, s96, 0x19000000
	s_addc_u32 s76, s97, 0
	s_add_u32 s77, s96, 0xd000000
	s_addc_u32 s78, s97, 0
	s_lshl_b32 s79, s0, 5
	v_mov_b32_e32 v3, 0
	s_lshl_b32 s0, s0, 12
	v_and_b32_e32 v2, 0x60, v232
	v_writelane_b32 v255, s1, 17
	s_mov_b32 s2, s91
	s_add_i32 s91, s0, 0
	v_lshl_add_u64 v[0:1], s[96:97], 0, v[2:3]
	s_mov_b64 s[0:1], 0x2800000
	v_lshl_add_u64 v[0:1], v[0:1], 0, s[0:1]
	v_lshlrev_b32_e32 v2, 8, v4
	s_movk_i32 s0, 0xf0f0
	v_ashrrev_i32_e32 v7, 3, v4
	v_and_b32_e32 v236, 0x70, v233
	v_bitop3_b32 v168, v2, s0, v233 bitop3:0xc8
	v_lshl_or_b32 v2, v7, 7, v236
	v_lshl_add_u64 v[8:9], s[96:97], 0, v[2:3]
	s_mov_b64 s[0:1], 0x1f500000
	v_lshl_add_u64 v[230:231], v[8:9], 0, s[0:1]
	v_lshrrev_b32_e32 v8, 4, v4
	s_movk_i32 s0, 0x190
	v_add_u32_e32 v4, 0x200, v4
	v_mul_lo_u32 v238, v8, s0
	v_lshrrev_b32_e32 v8, 4, v4
	v_mul_lo_u32 v239, v8, s0
	v_mul_lo_u32 v240, v7, s0
	s_movk_i32 s0, 0x90
	v_lshrrev_b32_e32 v4, 3, v4
	s_add_i32 s91, s91, 0x1a000
	v_mul_lo_u32 v242, v7, s0
	v_mul_lo_u32 v243, v4, s0
	v_lshlrev_b32_e32 v4, 1, v232
	s_and_b32 s0, s2, 0xffffff00
	v_lshl_or_b32 v172, v7, 15, v236
	v_and_b32_e32 v4, 8, v4
	v_and_b32_e32 v7, 4, v17
	v_and_b32_e32 v9, 19, v232
	s_cmpk_lg_i32 s0, 0x100
	v_lshrrev_b32_e32 v5, 5, v232
	v_add_u32_e32 v174, 0x200000, v172
	v_mov_b32_e32 v173, v3
	v_mov_b32_e32 v175, v3
	v_or3_b32 v4, v9, v4, v7
	s_cselect_b64 s[86:87], -1, 0
	s_cmpk_eq_i32 s0, 0x100
	s_mov_b64 s[0:1], 0x19000080
	v_and_b32_e32 v234, 31, v232
	v_lshlrev_b32_e32 v7, 4, v5
	v_mul_u32_u24_e32 v4, 0x190, v4
	v_lshl_add_u64 v[166:167], v[172:173], 0, s[0:1]
	v_lshl_add_u64 v[180:181], v[174:175], 0, s[0:1]
	s_mov_b64 s[0:1], 0x1f502000
	v_lshlrev_b32_e32 v6, 3, v5
	v_and_b32_e32 v235, 0xf0, v233
	v_add_u32_e32 v170, 0x20000, v168
	v_mov_b32_e32 v169, v3
	v_mov_b32_e32 v171, v3
	v_add_u32_e32 v8, 0, v240
	v_mul_u32_u24_e32 v9, 0x90, v234
	s_cselect_b64 s[88:89], -1, 0
	v_add3_u32 v245, 0, v4, v7
	s_cmpk_gt_u32 s2, 0xff
	v_lshlrev_b32_e32 v4, 2, v5
	v_or_b32_e32 v5, s79, v234
	v_lshl_add_u64 v[182:183], v[2:3], 0, s[0:1]
	s_mov_b64 s[0:1], 0x15040000
	v_add_u32_e32 v237, 0, v235
	v_add_u32_e32 v241, 0, v236
	v_add3_u32 v244, 0, v9, v7
	v_writelane_b32 v255, s2, 18
	s_cselect_b64 s[84:85], -1, 0
	v_sub_u32_e32 v246, v5, v6
	v_lshl_add_u64 v[184:185], v[168:169], 0, s[0:1]
	v_lshl_add_u64 v[186:187], v[170:171], 0, s[0:1]
	v_lshlrev_b32_e32 v188, 1, v4
	v_lshlrev_b32_e32 v190, 1, v6
	v_add_u32_e32 v247, v8, v236
	s_mov_b64 s[94:95], 0x80
	s_mov_b64 s[80:81], 0x40000
	v_mov_b32_e32 v189, v3
	v_mov_b32_e32 v191, v3
	v_mov_b32_e32 v248, 0xff800000
	s_and_b64 vcc, exec, s[86:87]
	s_cbranch_vccz .Lprio_skip
	s_setprio 1
.Lprio_skip:
	s_branch .LBB0_880
.LBB0_879:
	s_add_i32 s70, s72, s90
	s_cmpk_gt_i32 s70, 0x1ff
	s_cbranch_scc1 .LBB0_902

; __global__ void __launch_bounds__(512, 2) fwd_kernel(Args args) {
;     ...
;         for (int it = vcu; it < NB * NH * 16; it += G) {
;             const int bh = it >> 4, pi = it & 15, b = bh >> 4, h = bh & 15;
;             _Pragma("unroll 1") for (int half = 0; half < 2 * REPA; ++half) {
;                 const int qb = (half & 1) ? pi : 31 - pi;
;                 attn_unit<192, true, true>(lds, wave, WSF(O_CS) + (size_t)b * SEQ * 64, WSB(O_Q) + (size_t)b * SEQ * 3072 + h * DQKH, 3072, WSB(O_KN) + (size_t)b * SEQ * DM + h * 128, DM, WSB(O_KROPE) + (size_t)b * SEQ * 64, 64,
;                                      WSB(O_VT) + (size_t)h * 128 * MTOK + (size_t)b * SEQ, MTOK, WSB(O_ATTO) + (size_t)b * SEQ * DM + h * 128, DM, qb * 256, 4 * qb + 4, C);
;             }
;         }
;         { Gemm g{WSB(O_GY), WSB(O_WOLRU), MTOK, DM, DM, DM, DM, 0, wave}; StaticOrder S; S.init(MTOK, DM, G, bx);
.LBB0_902:
	s_setprio 0
	v_mov_b32_e32 v10, s79
	v_readlane_b32 s72, v254, 58
	v_readlane_b32 s92, v255, 15
	v_readlane_b32 s94, v255, 13
	v_readlane_b32 s73, v254, 59
	v_readlane_b32 s93, v255, 16
	v_readlane_b32 s95, v255, 14
	v_readlane_b32 s88, v254, 54
	v_readlane_b32 s62, v255, 10
	v_mov_b32_e32 v2, v233
	v_readlane_b32 s74, v254, 60
	v_readlane_b32 s75, v254, 61
	v_readlane_b32 s76, v254, 62
	v_readlane_b32 s77, v254, 63
	v_readlane_b32 s78, v255, 0
	v_readlane_b32 s79, v255, 1
	v_readlane_b32 s80, v255, 2
	v_readlane_b32 s81, v255, 3
	v_readlane_b32 s82, v255, 4
	v_readlane_b32 s83, v255, 5
	v_readlane_b32 s84, v255, 6
	v_readlane_b32 s85, v255, 7
	v_readlane_b32 s86, v255, 8
	v_readlane_b32 s87, v255, 9
	v_readlane_b32 s91, v255, 18
	v_readlane_b32 s89, v254, 55
	v_readlane_b32 s93, v254, 53
	v_readlane_b32 s95, v255, 12
	v_readlane_b32 s73, v254, 52
	v_readlane_b32 s63, v255, 11
	v_and_b32_e32 v240, 0x3ff, v253
	v_mbcnt_lo_u32_b32 v241, -1, 0
	v_lshrrev_b32_e32 v17, 1, v232
